# speedup vs baseline: 1.0073x; 1.0073x over previous
; __device__ __forceinline__ void finishSM(f32x16& p0, f32x16& p1, float alpha, float& l_reg, bf16x8& pa0, bf16x8& pa1, bf16x8& pa2, bf16x8& pa3) {
; #pragma unroll
;   for (int r = 0; r < 16; ++r) p1[r] = __builtin_amdgcn_exp2f(p1[r]);
;   float ps = 0;
; #pragma unroll
;   for (int r = 0; r < 16; ++r) ps += p0[r];
; #pragma unroll
;   for (int r = 0; r < 16; ++r) ps += p1[r];
;   { auto rr = __builtin_amdgcn_permlane32_swap(__float_as_uint(ps), __float_as_uint(ps), false, false);
;     ps = __uint_as_float(rr[0]) + __uint_as_float(rr[1]); }
;   l_reg = l_reg * alpha + ps;
;     ...
;   PK4(p0, 0, pa0); PK4(p0, 8, pa1); PK4(p1, 0, pa2); PK4(p1, 8, pa3);
;     ...
; }
; template <int BUFOFF>
; __device__ __forceinline__ void qkt_mla(f32x16& p0, f32x16& p1, const int* ka, const bf16x8* qr, const char* qlds) {
;   typedef __attribute__((address_space(3))) const bf16x8* lp;
;   p0 = f32x16{}; p1 = f32x16{};
; #pragma unroll
;   for (int d0 = 0; d0 < 12; ++d0) {
;     const int a = ka[d0 & 3] + (d0 >> 2) * 128 + BUFOFF;
;     const bf16x8 b0 = *(lp)(a), b1 = *(lp)(a + 12288);
;     bf16x8 qf;
;     qf = qr[d0];
;     p0 = __builtin_amdgcn_mfma_f32_32x32x16_bf16(b0, qf, p0, 0, 0, 0);
;     p1 = __builtin_amdgcn_mfma_f32_32x32x16_bf16(b1, qf, p1, 0, 0, 0);
;   }
; }
.LBB0_115:
	s_mov_b32 s55, s43
	s_mov_b32 s43, s52
	v_readlane_b32 s58, v249, 37
	v_readlane_b32 s59, v249, 38
	s_add_u32 s56, s58, s47
	s_addc_u32 s57, s59, s50
	s_add_u32 s4, s56, 0x17060000
	s_addc_u32 s5, s57, 0
	s_add_u32 s58, s58, s14
	s_addc_u32 s59, s59, s15
	s_add_u32 s60, s58, 0x1a040000
	s_addc_u32 s61, s59, 0
	s_lshl_b32 s52, s54, 14
	s_add_i32 s62, s40, s52
	ds_read_b128 v[64:67], v169 offset:24576
	ds_read_b128 v[68:71], v169 offset:36864
	ds_read_b128 v[214:217], v190 offset:24576
	ds_read_b128 v[218:221], v190 offset:36864
	s_waitcnt lgkmcnt(0)
	v_mfma_f32_32x32x16_bf16 v[80:95], v[64:67], v[140:143], v[226:241]
	v_add_f32_e32 v144, v200, v145
	v_mfma_f32_32x32x16_bf16 v[64:79], v[68:71], v[140:143], v[226:241]
	v_add_f32_e32 v243, v203, v210
	v_add_f32_e32 v244, v202, v208
	v_add_f32_e32 v245, v205, v212
	v_add_f32_e32 v246, v199, v211
	v_add_f32_e32 v247, v201, v213
	v_mfma_f32_32x32x16_bf16 v[80:95], v[214:217], v[136:139], v[80:95]
	v_add_f32_e32 v251, v204, v207
	v_add_f32_e32 v252, v206, v209
	v_mov_b32_e32 v196, v158
	v_add_f32_e32 v144, v172, v144
	v_add_f32_e32 v243, v173, v243
	v_mfma_f32_32x32x16_bf16 v[64:79], v[218:221], v[136:139], v[64:79]
	ds_read_b128 v[214:217], v193 offset:24576
	ds_read_b128 v[218:221], v193 offset:36864
	v_add_f32_e32 v244, v170, v244
	v_add_f32_e32 v245, v171, v245
	v_add_f32_e32 v246, v196, v246
	v_mov_b32_e32 v222, v147
	v_mov_b32_e32 v223, v154
	v_mov_b32_e32 v224, v155
	s_waitcnt lgkmcnt(0)
	v_mfma_f32_32x32x16_bf16 v[80:95], v[214:217], v[132:135], v[80:95]
	v_mfma_f32_32x32x16_bf16 v[64:79], v[218:221], v[132:135], v[64:79]
	ds_read_b128 v[214:217], v192 offset:24576
	ds_read_b128 v[218:221], v192 offset:36864
	s_waitcnt lgkmcnt(0)
	v_mfma_f32_32x32x16_bf16 v[80:95], v[214:217], v[128:131], v[80:95]
	v_mfma_f32_32x32x16_bf16 v[64:79], v[218:221], v[128:131], v[64:79]
	ds_read_b128 v[214:217], v169 offset:24704
	ds_read_b128 v[218:221], v169 offset:36992
	s_waitcnt lgkmcnt(0)
	v_mfma_f32_32x32x16_bf16 v[80:95], v[214:217], v[124:127], v[80:95]
	v_mfma_f32_32x32x16_bf16 v[64:79], v[218:221], v[124:127], v[64:79]
	ds_read_b128 v[214:217], v190 offset:24704
	ds_read_b128 v[218:221], v190 offset:36992
	s_waitcnt lgkmcnt(0)
	v_mfma_f32_32x32x16_bf16 v[80:95], v[214:217], v[120:123], v[80:95]
	v_mfma_f32_32x32x16_bf16 v[64:79], v[218:221], v[120:123], v[64:79]
	ds_read_b128 v[214:217], v193 offset:24704
	ds_read_b128 v[218:221], v193 offset:36992
	s_waitcnt lgkmcnt(0)
	v_mfma_f32_32x32x16_bf16 v[80:95], v[214:217], v[116:119], v[80:95]
	v_mfma_f32_32x32x16_bf16 v[64:79], v[218:221], v[116:119], v[64:79]
	ds_read_b128 v[214:217], v192 offset:24704
	ds_read_b128 v[218:221], v192 offset:36992
	s_waitcnt lgkmcnt(0)
	v_mfma_f32_32x32x16_bf16 v[80:95], v[214:217], v[112:115], v[80:95]
	v_mfma_f32_32x32x16_bf16 v[64:79], v[218:221], v[112:115], v[64:79]
	ds_read_b128 v[214:217], v169 offset:24832
	ds_read_b128 v[218:221], v169 offset:37120
	s_waitcnt lgkmcnt(0)
	v_mfma_f32_32x32x16_bf16 v[80:95], v[214:217], v[108:111], v[80:95]
	v_mfma_f32_32x32x16_bf16 v[64:79], v[218:221], v[108:111], v[64:79]
	ds_read_b128 v[214:217], v190 offset:24832
	ds_read_b128 v[218:221], v190 offset:37120
	s_waitcnt lgkmcnt(0)
	v_mfma_f32_32x32x16_bf16 v[80:95], v[214:217], v[104:107], v[80:95]
	v_mfma_f32_32x32x16_bf16 v[64:79], v[218:221], v[104:107], v[64:79]
	ds_read_b128 v[214:217], v193 offset:24832
	ds_read_b128 v[218:221], v193 offset:37120
	s_waitcnt lgkmcnt(0)
	v_mfma_f32_32x32x16_bf16 v[80:95], v[214:217], v[100:103], v[80:95]
	v_mfma_f32_32x32x16_bf16 v[64:79], v[218:221], v[100:103], v[64:79]
	ds_read_b128 v[214:217], v192 offset:24832
	ds_read_b128 v[218:221], v192 offset:37120
	s_waitcnt lgkmcnt(0)
	v_mfma_f32_32x32x16_bf16 v[80:95], v[214:217], v[96:99], v[80:95]
	v_mov_b32_e32 v214, v159
	v_mov_b32_e32 v215, v152
	v_mov_b32_e32 v216, v153
	v_mov_b32_e32 v217, v150
	v_add_f32_e32 v247, v214, v247
	v_add_f32_e32 v251, v215, v251
	v_add_f32_e32 v252, v216, v252
	v_mfma_f32_32x32x16_bf16 v[64:79], v[218:221], v[96:99], v[64:79]
	v_mov_b32_e32 v218, v151
	v_mov_b32_e32 v219, v148
	v_mov_b32_e32 v220, v149
	v_mov_b32_e32 v221, v146
	v_add_f32_e32 v144, v217, v144
	v_add_f32_e32 v243, v218, v243
	v_add_f32_e32 v244, v219, v244
	v_add_f32_e32 v245, v220, v245
	v_add_f32_e32 v246, v221, v246
	v_add_f32_e32 v247, v222, v247
	v_add_f32_e32 v251, v223, v251
	v_add_f32_e32 v252, v224, v252
	v_add_f32_e32 v144, v144, v243
	v_add_f32_e32 v244, v244, v245
	v_add_f32_e32 v246, v246, v247
	v_add_f32_e32 v251, v251, v252
	v_add_f32_e32 v144, v144, v244
	v_add_f32_e32 v246, v246, v251
	v_add_f32_e32 v158, v144, v246
	v_mov_b32_e32 v159, v158
	v_cvt_pk_bf16_f32 v144, v145, v210
	v_cvt_pk_bf16_f32 v145, v208, v212
	v_cvt_pk_bf16_f32 v146, v211, v213
	v_cvt_pk_bf16_f32 v147, v207, v209
	v_cvt_pk_bf16_f32 v148, v200, v203
	v_cvt_pk_bf16_f32 v149, v202, v205
	v_cvt_pk_bf16_f32 v150, v199, v201
	v_cvt_pk_bf16_f32 v151, v204, v206
	v_cvt_pk_bf16_f32 v152, v172, v173
	v_cvt_pk_bf16_f32 v153, v170, v171
	v_cvt_pk_bf16_f32 v154, v196, v214
	s_nop 1
	v_permlane32_swap_b32_e32 v158, v159
	v_cvt_pk_bf16_f32 v155, v215, v216
	v_cvt_pk_bf16_f32 v170, v217, v218
	v_cvt_pk_bf16_f32 v171, v219, v220
	v_cvt_pk_bf16_f32 v172, v221, v222
	v_cvt_pk_bf16_f32 v173, v223, v224
	s_mov_b32 m0, s41
	s_nop 0
	global_load_lds_dwordx4 v188, s[4:5]
	s_mov_b32 m0, s42
	s_nop 0
	global_load_lds_dwordx4 v189, s[4:5]
	s_add_i32 m0, s41, 0x4000
	s_nop 0
	global_load_lds_dwordx4 v191, s[4:5]
	s_mov_b32 m0, s62
	s_nop 0
	global_load_lds_dwordx4 v194, s[60:61]
	s_add_i32 m0, s62, 0x2000
	s_nop 0
	global_load_lds_dwordx4 v195, s[60:61]
	s_lshl_b32 s60, s43, 14
	v_add_u32_e32 v196, s60, v167
	ds_read_b64_tr_b16 v[200:201], v196 offset:0
	ds_read_b64_tr_b16 v[202:203], v196 offset:0x800
	ds_read_b64_tr_b16 v[204:205], v196 offset:0x1000
	ds_read_b64_tr_b16 v[206:207], v196 offset:0x1800
	ds_read_b64_tr_b16 v[208:209], v196 offset:0x2000
	ds_read_b64_tr_b16 v[210:211], v196 offset:0x2800
	ds_read_b64_tr_b16 v[212:213], v196 offset:0x3000
	ds_read_b64_tr_b16 v[214:215], v196 offset:0x3800
	s_waitcnt lgkmcnt(0)
; #define SBAR() __builtin_amdgcn_sched_barrier(0)
; template <int MLA>
; __device__ __forceinline__ void partialSM(f32x16& p0, f32x16& p1, float& m_reg, float& mn, float& alpha) {
;     ...
;   float pmax = p0[0];
; #pragma unroll
;   for (int r = 1; r < 16; ++r) pmax = fmaxf(pmax, p0[r]);
; #pragma unroll
;   for (int r = 0; r < 16; ++r) pmax = fmaxf(pmax, p1[r]);
;   { auto rr = __builtin_amdgcn_permlane32_swap(__float_as_uint(pmax), __float_as_uint(pmax), false, false);
;     pmax = fmaxf(__uint_as_float(rr[0]), __uint_as_float(rr[1])); }
;   if (__builtin_expect(__all(pmax - m_reg <= THR / SCALE), 1)) { mn = m_reg; alpha = 1.f; }
;   else { mn = fmaxf(m_reg, pmax); alpha = __builtin_amdgcn_exp2f((m_reg - mn) * C); m_reg = mn; }
;   float mnC = -mn * C;
; #pragma unroll
;   for (int r = 0; r < 16; ++r) p0[r] = fmaf(p0[r], C, mnC);
; #pragma unroll
;   for (int r = 0; r < 16; ++r) p1[r] = fmaf(p1[r], C, mnC);
; template <int D0> __device__ __forceinline__ void pv_one_t(f32x16& od, int vb, bf16x8 pa0, bf16x8 pa1, bf16x8 pa2, bf16x8 pa3) {
;   const s16x4 l0 = tr_read<v_rd_off(D0, 0, 0)>(vb), h0 = tr_read<v_rd_off(D0, 0, 1)>(vb), l1 = tr_read<v_rd_off(D0, 1, 0)>(vb), h1 = tr_read<v_rd_off(D0, 1, 1)>(vb);
;   const s16x4 l2 = tr_read<v_rd_off(D0, 2, 0)>(vb), h2 = tr_read<v_rd_off(D0, 2, 1)>(vb), l3 = tr_read<v_rd_off(D0, 3, 0)>(vb), h3 = tr_read<v_rd_off(D0, 3, 1)>(vb);
;   asm volatile("s_waitcnt lgkmcnt(0)" ::: "memory"); SBAR();
;     ...
;   od = __builtin_amdgcn_mfma_f32_32x32x16_bf16(PK(l0, h0), pa0, od, 0, 0, 0);
;   od = __builtin_amdgcn_mfma_f32_32x32x16_bf16(PK(l1, h1), pa1, od, 0, 0, 0);
;   od = __builtin_amdgcn_mfma_f32_32x32x16_bf16(PK(l2, h2), pa2, od, 0, 0, 0);
;   od = __builtin_amdgcn_mfma_f32_32x32x16_bf16(PK(l3, h3), pa3, od, 0, 0, 0);
;     ...
; }
; __device__ __forceinline__ void pv_d0_t(f32x16* o, int vb, bf16x8 pa0, bf16x8 pa1, bf16x8 pa2, bf16x8 pa3) {
;   pv_one_t<0>(o[0], vb, pa0, pa1, pa2, pa3); pv_one_t<1>(o[1], vb, pa0, pa1, pa2, pa3); pv_one_t<2>(o[2], vb, pa0, pa1, pa2, pa3); pv_one_t<3>(o[3], vb, pa0, pa1, pa2, pa3);
; }
	s_nop 0
	v_mfma_f32_32x32x16_bf16 v[0:15], v[200:203], v[144:147], v[0:15]
	ds_read_b64_tr_b16 v[200:201], v196 offset:0x200
	ds_read_b64_tr_b16 v[202:203], v196 offset:0xa00
	v_mfma_f32_32x32x16_bf16 v[0:15], v[204:207], v[148:151], v[0:15]
	ds_read_b64_tr_b16 v[204:205], v196 offset:0x1200
	ds_read_b64_tr_b16 v[206:207], v196 offset:0x1a00
	v_mfma_f32_32x32x16_bf16 v[0:15], v[208:211], v[152:155], v[0:15]
	ds_read_b64_tr_b16 v[208:209], v196 offset:0x2200
	ds_read_b64_tr_b16 v[210:211], v196 offset:0x2a00
	v_mfma_f32_32x32x16_bf16 v[0:15], v[212:215], v[170:173], v[0:15]
	ds_read_b64_tr_b16 v[212:213], v196 offset:0x3200
	ds_read_b64_tr_b16 v[214:215], v196 offset:0x3a00
	s_waitcnt lgkmcnt(0)
	v_mfma_f32_32x32x16_bf16 v[48:63], v[200:203], v[144:147], v[48:63]
	ds_read_b64_tr_b16 v[200:201], v196 offset:0x400
	ds_read_b64_tr_b16 v[202:203], v196 offset:0xc00
	v_mfma_f32_32x32x16_bf16 v[48:63], v[204:207], v[148:151], v[48:63]
	ds_read_b64_tr_b16 v[204:205], v196 offset:0x1400
	ds_read_b64_tr_b16 v[206:207], v196 offset:0x1c00
	v_mfma_f32_32x32x16_bf16 v[48:63], v[208:211], v[152:155], v[48:63]
	ds_read_b64_tr_b16 v[208:209], v196 offset:0x2400
	ds_read_b64_tr_b16 v[210:211], v196 offset:0x2c00
	v_mfma_f32_32x32x16_bf16 v[48:63], v[212:215], v[170:173], v[48:63]
	ds_read_b64_tr_b16 v[212:213], v196 offset:0x3400
	ds_read_b64_tr_b16 v[214:215], v196 offset:0x3c00
	s_waitcnt lgkmcnt(0)
	v_mfma_f32_32x32x16_bf16 v[32:47], v[200:203], v[144:147], v[32:47]
	ds_read_b64_tr_b16 v[200:201], v196 offset:0x600
	ds_read_b64_tr_b16 v[202:203], v196 offset:0xe00
	v_mfma_f32_32x32x16_bf16 v[32:47], v[204:207], v[148:151], v[32:47]
	ds_read_b64_tr_b16 v[204:205], v196 offset:0x1600
	ds_read_b64_tr_b16 v[206:207], v196 offset:0x1e00
	v_mfma_f32_32x32x16_bf16 v[32:47], v[208:211], v[152:155], v[32:47]
	ds_read_b64_tr_b16 v[208:209], v196 offset:0x2600
	ds_read_b64_tr_b16 v[210:211], v196 offset:0x2e00
	v_mfma_f32_32x32x16_bf16 v[32:47], v[212:215], v[170:173], v[32:47]
	ds_read_b64_tr_b16 v[212:213], v196 offset:0x3600
	ds_read_b64_tr_b16 v[214:215], v196 offset:0x3e00
	s_waitcnt lgkmcnt(0)
	v_mfma_f32_32x32x16_bf16 v[16:31], v[200:203], v[144:147], v[16:31]
	v_max_f32_e32 v144, v80, v81
	v_max3_f32 v144, v144, v82, v83
	v_max3_f32 v144, v144, v84, v85
	v_max3_f32 v144, v144, v86, v87
	v_max3_f32 v144, v144, v88, v89
	v_max3_f32 v144, v144, v90, v91
	v_max3_f32 v144, v144, v92, v93
	v_mfma_f32_32x32x16_bf16 v[16:31], v[204:207], v[148:151], v[16:31]
	v_max3_f32 v144, v144, v94, v95
	v_max3_f32 v144, v144, v64, v65
	v_max3_f32 v144, v144, v66, v67
	v_max3_f32 v144, v144, v68, v69
	v_max3_f32 v144, v144, v70, v71
	v_max3_f32 v144, v144, v72, v73
	v_max3_f32 v144, v144, v74, v75
	v_max3_f32 v144, v144, v76, v77
	v_mfma_f32_32x32x16_bf16 v[16:31], v[208:211], v[152:155], v[16:31]
	v_max3_f32 v144, v144, v78, v79
	v_mov_b32_e32 v145, v144
	s_nop 1
	v_permlane32_swap_b32_e32 v144, v145
	v_max_f32_e32 v144, v144, v145
	v_cmp_ge_f32_e32 vcc, s63, v144
	v_mfma_f32_32x32x16_bf16 v[16:31], v[212:215], v[170:173], v[16:31]
	s_cmp_eq_u64 vcc, exec
	s_cselect_b64 s[4:5], -1, 0
	s_waitcnt vmcnt(0) lgkmcnt(0)
	s_barrier
	s_cbranch_scc1 .Lal_c_m1
	v_max_f32_e32 v242, 0, v144
	v_exp_f32_e64 v152, -v242
	s_nop 0
	v_pk_mul_f32 v[14:15], v[14:15], v[152:153] op_sel_hi:[1,0]
	v_pk_mul_f32 v[12:13], v[12:13], v[152:153] op_sel_hi:[1,0]
	v_pk_mul_f32 v[10:11], v[10:11], v[152:153] op_sel_hi:[1,0]
	v_pk_mul_f32 v[8:9], v[8:9], v[152:153] op_sel_hi:[1,0]
	v_pk_mul_f32 v[6:7], v[6:7], v[152:153] op_sel_hi:[1,0]
	v_pk_mul_f32 v[4:5], v[4:5], v[152:153] op_sel_hi:[1,0]
	v_pk_mul_f32 v[2:3], v[2:3], v[152:153] op_sel_hi:[1,0]
	v_pk_mul_f32 v[0:1], v[0:1], v[152:153] op_sel_hi:[1,0]
	v_pk_mul_f32 v[62:63], v[62:63], v[152:153] op_sel_hi:[1,0]
	v_pk_mul_f32 v[60:61], v[60:61], v[152:153] op_sel_hi:[1,0]
	v_pk_mul_f32 v[58:59], v[58:59], v[152:153] op_sel_hi:[1,0]
	v_pk_mul_f32 v[56:57], v[56:57], v[152:153] op_sel_hi:[1,0]
	v_pk_mul_f32 v[54:55], v[54:55], v[152:153] op_sel_hi:[1,0]
	v_pk_mul_f32 v[52:53], v[52:53], v[152:153] op_sel_hi:[1,0]
	v_pk_mul_f32 v[50:51], v[50:51], v[152:153] op_sel_hi:[1,0]
	v_pk_mul_f32 v[48:49], v[48:49], v[152:153] op_sel_hi:[1,0]
	v_pk_mul_f32 v[46:47], v[46:47], v[152:153] op_sel_hi:[1,0]
	v_pk_mul_f32 v[44:45], v[44:45], v[152:153] op_sel_hi:[1,0]
	v_pk_mul_f32 v[42:43], v[42:43], v[152:153] op_sel_hi:[1,0]
	v_pk_mul_f32 v[40:41], v[40:41], v[152:153] op_sel_hi:[1,0]
	v_pk_mul_f32 v[38:39], v[38:39], v[152:153] op_sel_hi:[1,0]
	v_pk_mul_f32 v[36:37], v[36:37], v[152:153] op_sel_hi:[1,0]
	v_pk_mul_f32 v[34:35], v[34:35], v[152:153] op_sel_hi:[1,0]
	v_pk_mul_f32 v[32:33], v[32:33], v[152:153] op_sel_hi:[1,0]
	v_pk_mul_f32 v[30:31], v[30:31], v[152:153] op_sel_hi:[1,0]
	v_pk_mul_f32 v[28:29], v[28:29], v[152:153] op_sel_hi:[1,0]
	v_pk_mul_f32 v[26:27], v[26:27], v[152:153] op_sel_hi:[1,0]
	v_pk_mul_f32 v[24:25], v[24:25], v[152:153] op_sel_hi:[1,0]
	v_pk_mul_f32 v[22:23], v[22:23], v[152:153] op_sel_hi:[1,0]
	v_pk_mul_f32 v[20:21], v[20:21], v[152:153] op_sel_hi:[1,0]
	v_pk_mul_f32 v[18:19], v[18:19], v[152:153] op_sel_hi:[1,0]
	v_pk_mul_f32 v[16:17], v[16:17], v[152:153] op_sel_hi:[1,0]
	v_sub_f32_e32 v80, v80, v242
	v_sub_f32_e32 v81, v81, v242
	v_sub_f32_e32 v82, v82, v242
	v_sub_f32_e32 v83, v83, v242
	v_sub_f32_e32 v84, v84, v242
	v_sub_f32_e32 v85, v85, v242
	v_sub_f32_e32 v86, v86, v242
	v_sub_f32_e32 v87, v87, v242
	v_sub_f32_e32 v88, v88, v242
	v_sub_f32_e32 v89, v89, v242
	v_sub_f32_e32 v90, v90, v242
	v_sub_f32_e32 v91, v91, v242
	v_sub_f32_e32 v92, v92, v242
	v_sub_f32_e32 v93, v93, v242
	v_sub_f32_e32 v94, v94, v242
	v_sub_f32_e32 v95, v95, v242
	v_sub_f32_e32 v64, v64, v242
	v_sub_f32_e32 v65, v65, v242
	v_sub_f32_e32 v66, v66, v242
	v_sub_f32_e32 v67, v67, v242
	v_sub_f32_e32 v68, v68, v242
	v_sub_f32_e32 v69, v69, v242
	v_sub_f32_e32 v70, v70, v242
	v_sub_f32_e32 v71, v71, v242
	v_sub_f32_e32 v72, v72, v242
	v_sub_f32_e32 v73, v73, v242
	v_sub_f32_e32 v74, v74, v242
	v_sub_f32_e32 v75, v75, v242
	v_sub_f32_e32 v76, v76, v242
	v_sub_f32_e32 v77, v77, v242
	v_sub_f32_e32 v78, v78, v242
	v_sub_f32_e32 v79, v79, v242
	v_sub_f32_e32 v226, v226, v242
	v_sub_f32_e32 v227, v227, v242
	v_sub_f32_e32 v228, v228, v242
	v_sub_f32_e32 v229, v229, v242
	v_sub_f32_e32 v230, v230, v242
	v_sub_f32_e32 v231, v231, v242
	v_sub_f32_e32 v232, v232, v242
	v_sub_f32_e32 v233, v233, v242
	v_sub_f32_e32 v234, v234, v242
	v_sub_f32_e32 v235, v235, v242
	v_sub_f32_e32 v236, v236, v242
	v_sub_f32_e32 v237, v237, v242
	v_sub_f32_e32 v238, v238, v242
	v_sub_f32_e32 v239, v239, v242
	v_sub_f32_e32 v240, v240, v242
	v_sub_f32_e32 v241, v241, v242
	s_branch .LBB0_117

; __device__ __forceinline__ void finishSM(f32x16& p0, f32x16& p1, float alpha, float& l_reg, bf16x8& pa0, bf16x8& pa1, bf16x8& pa2, bf16x8& pa3) {
; #pragma unroll
;   for (int r = 0; r < 16; ++r) p1[r] = __builtin_amdgcn_exp2f(p1[r]);
;   float ps = 0;
; #pragma unroll
;   for (int r = 0; r < 16; ++r) ps += p0[r];
; #pragma unroll
;   for (int r = 0; r < 16; ++r) ps += p1[r];
;   { auto rr = __builtin_amdgcn_permlane32_swap(__float_as_uint(ps), __float_as_uint(ps), false, false);
;     ps = __uint_as_float(rr[0]) + __uint_as_float(rr[1]); }
;   l_reg = l_reg * alpha + ps;
;     ...
;   PK4(p0, 0, pa0); PK4(p0, 8, pa1); PK4(p1, 0, pa2); PK4(p1, 8, pa3);
;     ...
; }
; template <int BUFOFF>
; __device__ __forceinline__ void qkt_mla(f32x16& p0, f32x16& p1, const int* ka, const bf16x8* qr, const char* qlds) {
;   typedef __attribute__((address_space(3))) const bf16x8* lp;
;   p0 = f32x16{}; p1 = f32x16{};
; #pragma unroll
;   for (int d0 = 0; d0 < 12; ++d0) {
;     const int a = ka[d0 & 3] + (d0 >> 2) * 128 + BUFOFF;
;     const bf16x8 b0 = *(lp)(a), b1 = *(lp)(a + 12288);
;     bf16x8 qf;
;     qf = qr[d0];
;     p0 = __builtin_amdgcn_mfma_f32_32x32x16_bf16(b0, qf, p0, 0, 0, 0);
;     p1 = __builtin_amdgcn_mfma_f32_32x32x16_bf16(b1, qf, p1, 0, 0, 0);
;   }
; }
.LBB0_117:
	s_add_u32 s4, s56, 0x17090000
	s_addc_u32 s5, s57, 0
	s_add_u32 s56, s58, 0x1a060000
	s_addc_u32 s57, s59, 0
	s_add_i32 s58, s40, s60
	v_exp_f32_e32 v155, v64
	v_exp_f32_e32 v170, v65
	v_exp_f32_e32 v171, v66
	v_exp_f32_e32 v172, v67
	v_exp_f32_e32 v173, v68
	v_exp_f32_e32 v197, v69
	v_exp_f32_e32 v199, v70
	v_exp_f32_e32 v200, v71
	v_exp_f32_e32 v201, v72
	v_exp_f32_e32 v202, v73
	v_exp_f32_e32 v203, v74
	v_exp_f32_e32 v204, v75
	v_exp_f32_e32 v205, v76
	v_exp_f32_e32 v222, v77
	v_exp_f32_e32 v223, v78
	v_exp_f32_e32 v154, v79
	v_exp_f32_e32 v206, v80
	v_exp_f32_e32 v207, v81
	v_exp_f32_e32 v208, v82
	v_exp_f32_e32 v209, v83
	v_exp_f32_e32 v210, v84
	v_exp_f32_e32 v211, v85
	v_exp_f32_e32 v212, v86
	v_exp_f32_e32 v213, v87
	v_exp_f32_e32 v214, v88
	v_exp_f32_e32 v215, v89
	v_exp_f32_e32 v216, v90
	v_exp_f32_e32 v217, v91
	v_exp_f32_e32 v218, v92
	v_exp_f32_e32 v219, v93
	v_exp_f32_e32 v220, v94
	v_exp_f32_e32 v221, v95
	ds_read_b128 v[64:67], v169
	ds_read_b128 v[68:71], v169 offset:12288
	ds_read_b128 v[144:147], v190
	ds_read_b128 v[148:151], v190 offset:12288
	v_mov_b32_e32 v224, v155
	s_waitcnt lgkmcnt(0)
	v_mfma_f32_32x32x16_bf16 v[80:95], v[64:67], v[140:143], v[226:241]
	v_mfma_f32_32x32x16_bf16 v[64:79], v[68:71], v[140:143], v[226:241]
	v_mov_b32_e32 v225, v154
	v_mfma_f32_32x32x16_bf16 v[80:95], v[144:147], v[136:139], v[80:95]
	v_mfma_f32_32x32x16_bf16 v[64:79], v[148:151], v[136:139], v[64:79]
	ds_read_b128 v[144:147], v193
	ds_read_b128 v[148:151], v193 offset:12288
	s_waitcnt lgkmcnt(0)
	v_mfma_f32_32x32x16_bf16 v[80:95], v[144:147], v[132:135], v[80:95]
	v_mfma_f32_32x32x16_bf16 v[64:79], v[148:151], v[132:135], v[64:79]
	ds_read_b128 v[144:147], v192
	ds_read_b128 v[148:151], v192 offset:12288
	s_waitcnt lgkmcnt(0)
	v_mfma_f32_32x32x16_bf16 v[80:95], v[144:147], v[128:131], v[80:95]
	v_mfma_f32_32x32x16_bf16 v[64:79], v[148:151], v[128:131], v[64:79]
	ds_read_b128 v[144:147], v169 offset:128
	ds_read_b128 v[148:151], v169 offset:12416
	s_waitcnt lgkmcnt(0)
	v_mfma_f32_32x32x16_bf16 v[80:95], v[144:147], v[124:127], v[80:95]
	v_mfma_f32_32x32x16_bf16 v[64:79], v[148:151], v[124:127], v[64:79]
	ds_read_b128 v[144:147], v190 offset:128
	ds_read_b128 v[148:151], v190 offset:12416
	s_waitcnt lgkmcnt(0)
	v_mfma_f32_32x32x16_bf16 v[80:95], v[144:147], v[120:123], v[80:95]
	v_mfma_f32_32x32x16_bf16 v[64:79], v[148:151], v[120:123], v[64:79]
	ds_read_b128 v[144:147], v193 offset:128
	ds_read_b128 v[148:151], v193 offset:12416
	s_waitcnt lgkmcnt(0)
	v_mfma_f32_32x32x16_bf16 v[80:95], v[144:147], v[116:119], v[80:95]
	v_mfma_f32_32x32x16_bf16 v[64:79], v[148:151], v[116:119], v[64:79]
	ds_read_b128 v[144:147], v192 offset:128
	ds_read_b128 v[148:151], v192 offset:12416
	s_waitcnt lgkmcnt(0)
	v_mfma_f32_32x32x16_bf16 v[80:95], v[144:147], v[112:115], v[80:95]
	v_mfma_f32_32x32x16_bf16 v[64:79], v[148:151], v[112:115], v[64:79]
	ds_read_b128 v[144:147], v169 offset:256
	ds_read_b128 v[148:151], v169 offset:12544
	s_waitcnt lgkmcnt(0)
	v_mfma_f32_32x32x16_bf16 v[80:95], v[144:147], v[108:111], v[80:95]
	v_mfma_f32_32x32x16_bf16 v[64:79], v[148:151], v[108:111], v[64:79]
	ds_read_b128 v[144:147], v190 offset:256
	ds_read_b128 v[148:151], v190 offset:12544
	s_waitcnt lgkmcnt(0)
	v_mfma_f32_32x32x16_bf16 v[80:95], v[144:147], v[104:107], v[80:95]
	v_mfma_f32_32x32x16_bf16 v[64:79], v[148:151], v[104:107], v[64:79]
	ds_read_b128 v[144:147], v193 offset:256
	ds_read_b128 v[148:151], v193 offset:12544
	s_waitcnt lgkmcnt(0)
	v_mfma_f32_32x32x16_bf16 v[80:95], v[144:147], v[100:103], v[80:95]
	v_mfma_f32_32x32x16_bf16 v[64:79], v[148:151], v[100:103], v[64:79]
	ds_read_b128 v[144:147], v192 offset:256
	ds_read_b128 v[148:151], v192 offset:12544
	s_waitcnt lgkmcnt(0)
	v_mfma_f32_32x32x16_bf16 v[80:95], v[144:147], v[96:99], v[80:95]
	v_add_f32_e32 v144, v214, v206
	v_add_f32_e32 v243, v215, v207
	v_add_f32_e32 v244, v216, v208
	v_add_f32_e32 v245, v217, v209
	v_add_f32_e32 v246, v218, v210
	v_add_f32_e32 v247, v219, v211
	v_add_f32_e32 v251, v220, v212
	v_add_f32_e32 v252, v221, v213
	v_add_f32_e32 v144, v224, v144
	v_add_f32_e32 v243, v170, v243
	v_add_f32_e32 v244, v171, v244
	v_add_f32_e32 v245, v172, v245
	v_add_f32_e32 v246, v173, v246
	v_add_f32_e32 v247, v197, v247
	v_add_f32_e32 v251, v199, v251
	v_add_f32_e32 v252, v200, v252
	v_add_f32_e32 v144, v201, v144
	v_add_f32_e32 v243, v202, v243
	v_mfma_f32_32x32x16_bf16 v[64:79], v[148:151], v[96:99], v[64:79]
	v_add_f32_e32 v244, v203, v244
	v_add_f32_e32 v245, v204, v245
	v_add_f32_e32 v246, v205, v246
	v_add_f32_e32 v247, v222, v247
	v_add_f32_e32 v251, v223, v251
	v_add_f32_e32 v252, v225, v252
	v_add_f32_e32 v144, v144, v243
	v_add_f32_e32 v244, v244, v245
	v_add_f32_e32 v246, v246, v247
	v_add_f32_e32 v251, v251, v252
	v_add_f32_e32 v144, v144, v244
	v_add_f32_e32 v246, v246, v251
	v_add_f32_e32 v154, v144, v246
	v_mov_b32_e32 v155, v154
	v_cvt_pk_bf16_f32 v144, v206, v207
	v_cvt_pk_bf16_f32 v145, v208, v209
	v_cvt_pk_bf16_f32 v146, v210, v211
	v_cvt_pk_bf16_f32 v147, v212, v213
	s_nop 1
	v_permlane32_swap_b32_e32 v154, v155
	v_cvt_pk_bf16_f32 v148, v214, v215
	v_cvt_pk_bf16_f32 v149, v216, v217
	v_cvt_pk_bf16_f32 v150, v218, v219
	v_cvt_pk_bf16_f32 v151, v220, v221
	v_cvt_pk_bf16_f32 v170, v224, v170
	v_cvt_pk_bf16_f32 v171, v171, v172
	v_cvt_pk_bf16_f32 v172, v173, v197
	v_cvt_pk_bf16_f32 v173, v199, v200
	v_cvt_pk_bf16_f32 v200, v201, v202
	v_cvt_pk_bf16_f32 v201, v203, v204
	v_cvt_pk_bf16_f32 v202, v205, v222
	v_cvt_pk_bf16_f32 v203, v223, v225
	s_nop 0
	s_mov_b32 m0, s16
	s_nop 0
	global_load_lds_dwordx4 v188, s[4:5]
	s_mov_b32 m0, s17
	s_nop 0
	global_load_lds_dwordx4 v189, s[4:5]
	s_mov_b32 m0, s44
	s_nop 0
	global_load_lds_dwordx4 v191, s[4:5]
	s_mov_b32 m0, s58
	s_nop 0
	global_load_lds_dwordx4 v194, s[56:57]
	s_add_i32 m0, s58, 0x2000
	s_nop 0
	global_load_lds_dwordx4 v195, s[56:57]
	v_lshl_add_u32 v197, s55, 14, v167
	ds_read_b64_tr_b16 v[204:205], v197 offset:0
	ds_read_b64_tr_b16 v[206:207], v197 offset:0x800
	ds_read_b64_tr_b16 v[208:209], v197 offset:0x1000
	ds_read_b64_tr_b16 v[210:211], v197 offset:0x1800
	ds_read_b64_tr_b16 v[212:213], v197 offset:0x2000
	ds_read_b64_tr_b16 v[214:215], v197 offset:0x2800
	ds_read_b64_tr_b16 v[216:217], v197 offset:0x3000
	ds_read_b64_tr_b16 v[218:219], v197 offset:0x3800
	s_waitcnt lgkmcnt(0)
; #define SBAR() __builtin_amdgcn_sched_barrier(0)
; template <int MLA>
; __device__ __forceinline__ void partialSM(f32x16& p0, f32x16& p1, float& m_reg, float& mn, float& alpha) {
;     ...
;   float pmax = p0[0];
; #pragma unroll
;   for (int r = 1; r < 16; ++r) pmax = fmaxf(pmax, p0[r]);
; #pragma unroll
;   for (int r = 0; r < 16; ++r) pmax = fmaxf(pmax, p1[r]);
;   { auto rr = __builtin_amdgcn_permlane32_swap(__float_as_uint(pmax), __float_as_uint(pmax), false, false);
;     pmax = fmaxf(__uint_as_float(rr[0]), __uint_as_float(rr[1])); }
;   if (__builtin_expect(__all(pmax - m_reg <= THR / SCALE), 1)) { mn = m_reg; alpha = 1.f; }
;   else { mn = fmaxf(m_reg, pmax); alpha = __builtin_amdgcn_exp2f((m_reg - mn) * C); m_reg = mn; }
;   float mnC = -mn * C;
; #pragma unroll
;   for (int r = 0; r < 16; ++r) p0[r] = fmaf(p0[r], C, mnC);
; #pragma unroll
;   for (int r = 0; r < 16; ++r) p1[r] = fmaf(p1[r], C, mnC);
; template <int D0> __device__ __forceinline__ void pv_one_t(f32x16& od, int vb, bf16x8 pa0, bf16x8 pa1, bf16x8 pa2, bf16x8 pa3) {
;   const s16x4 l0 = tr_read<v_rd_off(D0, 0, 0)>(vb), h0 = tr_read<v_rd_off(D0, 0, 1)>(vb), l1 = tr_read<v_rd_off(D0, 1, 0)>(vb), h1 = tr_read<v_rd_off(D0, 1, 1)>(vb);
;   const s16x4 l2 = tr_read<v_rd_off(D0, 2, 0)>(vb), h2 = tr_read<v_rd_off(D0, 2, 1)>(vb), l3 = tr_read<v_rd_off(D0, 3, 0)>(vb), h3 = tr_read<v_rd_off(D0, 3, 1)>(vb);
;   asm volatile("s_waitcnt lgkmcnt(0)" ::: "memory"); SBAR();
;     ...
;   od = __builtin_amdgcn_mfma_f32_32x32x16_bf16(PK(l0, h0), pa0, od, 0, 0, 0);
;   od = __builtin_amdgcn_mfma_f32_32x32x16_bf16(PK(l1, h1), pa1, od, 0, 0, 0);
;   od = __builtin_amdgcn_mfma_f32_32x32x16_bf16(PK(l2, h2), pa2, od, 0, 0, 0);
;   od = __builtin_amdgcn_mfma_f32_32x32x16_bf16(PK(l3, h3), pa3, od, 0, 0, 0);
;     ...
; }
; __device__ __forceinline__ void pv_d0_t(f32x16* o, int vb, bf16x8 pa0, bf16x8 pa1, bf16x8 pa2, bf16x8 pa3) {
;   pv_one_t<0>(o[0], vb, pa0, pa1, pa2, pa3); pv_one_t<1>(o[1], vb, pa0, pa1, pa2, pa3); pv_one_t<2>(o[2], vb, pa0, pa1, pa2, pa3); pv_one_t<3>(o[3], vb, pa0, pa1, pa2, pa3);
; }
	s_nop 0
	v_mfma_f32_32x32x16_bf16 v[0:15], v[204:207], v[144:147], v[0:15]
	ds_read_b64_tr_b16 v[204:205], v197 offset:0x200
	ds_read_b64_tr_b16 v[206:207], v197 offset:0xa00
	v_mfma_f32_32x32x16_bf16 v[0:15], v[208:211], v[148:151], v[0:15]
	ds_read_b64_tr_b16 v[208:209], v197 offset:0x1200
	ds_read_b64_tr_b16 v[210:211], v197 offset:0x1a00
	v_mfma_f32_32x32x16_bf16 v[0:15], v[212:215], v[170:173], v[0:15]
	ds_read_b64_tr_b16 v[212:213], v197 offset:0x2200
	ds_read_b64_tr_b16 v[214:215], v197 offset:0x2a00
	v_mfma_f32_32x32x16_bf16 v[0:15], v[216:219], v[200:203], v[0:15]
	ds_read_b64_tr_b16 v[216:217], v197 offset:0x3200
	ds_read_b64_tr_b16 v[218:219], v197 offset:0x3a00
	s_waitcnt lgkmcnt(0)
	v_mfma_f32_32x32x16_bf16 v[48:63], v[204:207], v[144:147], v[48:63]
	ds_read_b64_tr_b16 v[204:205], v197 offset:0x400
	ds_read_b64_tr_b16 v[206:207], v197 offset:0xc00
	v_mfma_f32_32x32x16_bf16 v[48:63], v[208:211], v[148:151], v[48:63]
	ds_read_b64_tr_b16 v[208:209], v197 offset:0x1400
	ds_read_b64_tr_b16 v[210:211], v197 offset:0x1c00
	v_mfma_f32_32x32x16_bf16 v[48:63], v[212:215], v[170:173], v[48:63]
	ds_read_b64_tr_b16 v[212:213], v197 offset:0x2400
	ds_read_b64_tr_b16 v[214:215], v197 offset:0x2c00
	v_mfma_f32_32x32x16_bf16 v[48:63], v[216:219], v[200:203], v[48:63]
	ds_read_b64_tr_b16 v[216:217], v197 offset:0x3400
	ds_read_b64_tr_b16 v[218:219], v197 offset:0x3c00
	s_waitcnt lgkmcnt(0)
	v_mfma_f32_32x32x16_bf16 v[32:47], v[204:207], v[144:147], v[32:47]
	ds_read_b64_tr_b16 v[204:205], v197 offset:0x600
	ds_read_b64_tr_b16 v[206:207], v197 offset:0xe00
	v_mfma_f32_32x32x16_bf16 v[32:47], v[208:211], v[148:151], v[32:47]
	ds_read_b64_tr_b16 v[208:209], v197 offset:0x1600
	ds_read_b64_tr_b16 v[210:211], v197 offset:0x1e00
	v_mfma_f32_32x32x16_bf16 v[32:47], v[212:215], v[170:173], v[32:47]
	ds_read_b64_tr_b16 v[212:213], v197 offset:0x2600
	ds_read_b64_tr_b16 v[214:215], v197 offset:0x2e00
	v_mfma_f32_32x32x16_bf16 v[32:47], v[216:219], v[200:203], v[32:47]
	ds_read_b64_tr_b16 v[216:217], v197 offset:0x3600
	ds_read_b64_tr_b16 v[218:219], v197 offset:0x3e00
	s_waitcnt lgkmcnt(0)
	v_mfma_f32_32x32x16_bf16 v[16:31], v[204:207], v[144:147], v[16:31]
	v_max_f32_e32 v144, v80, v81
	v_max3_f32 v144, v144, v82, v83
	v_max3_f32 v144, v144, v84, v85
	v_max3_f32 v144, v144, v86, v87
	v_max3_f32 v144, v144, v88, v89
	v_max3_f32 v144, v144, v90, v91
	v_max3_f32 v144, v144, v92, v93
	v_mfma_f32_32x32x16_bf16 v[16:31], v[208:211], v[148:151], v[16:31]
	v_max3_f32 v144, v144, v94, v95
	v_max3_f32 v144, v144, v64, v65
	v_max3_f32 v144, v144, v66, v67
	v_max3_f32 v144, v144, v68, v69
	v_max3_f32 v144, v144, v70, v71
	v_max3_f32 v144, v144, v72, v73
	v_max3_f32 v144, v144, v74, v75
	v_max3_f32 v144, v144, v76, v77
	v_mfma_f32_32x32x16_bf16 v[16:31], v[212:215], v[170:173], v[16:31]
	v_max3_f32 v144, v144, v78, v79
	v_mov_b32_e32 v145, v144
	s_nop 1
	v_permlane32_swap_b32_e32 v144, v145
	v_max_f32_e32 v144, v144, v145
	v_cmp_ge_f32_e32 vcc, s63, v144
	v_mfma_f32_32x32x16_bf16 v[16:31], v[216:219], v[200:203], v[16:31]
	s_cmp_eq_u64 vcc, exec
	s_cselect_b64 s[4:5], -1, 0
	s_waitcnt vmcnt(0) lgkmcnt(0)
	s_barrier
	s_cbranch_scc1 .Lal_c_m2
	v_max_f32_e32 v242, 0, v144
	v_exp_f32_e64 v144, -v242
	s_nop 0
	v_pk_mul_f32 v[14:15], v[14:15], v[144:145] op_sel_hi:[1,0]
	v_pk_mul_f32 v[12:13], v[12:13], v[144:145] op_sel_hi:[1,0]
	v_pk_mul_f32 v[10:11], v[10:11], v[144:145] op_sel_hi:[1,0]
	v_pk_mul_f32 v[8:9], v[8:9], v[144:145] op_sel_hi:[1,0]
	v_pk_mul_f32 v[6:7], v[6:7], v[144:145] op_sel_hi:[1,0]
	v_pk_mul_f32 v[4:5], v[4:5], v[144:145] op_sel_hi:[1,0]
	v_pk_mul_f32 v[2:3], v[2:3], v[144:145] op_sel_hi:[1,0]
	v_pk_mul_f32 v[0:1], v[0:1], v[144:145] op_sel_hi:[1,0]
	v_pk_mul_f32 v[62:63], v[62:63], v[144:145] op_sel_hi:[1,0]
	v_pk_mul_f32 v[60:61], v[60:61], v[144:145] op_sel_hi:[1,0]
	v_pk_mul_f32 v[58:59], v[58:59], v[144:145] op_sel_hi:[1,0]
	v_pk_mul_f32 v[56:57], v[56:57], v[144:145] op_sel_hi:[1,0]
	v_pk_mul_f32 v[54:55], v[54:55], v[144:145] op_sel_hi:[1,0]
	v_pk_mul_f32 v[52:53], v[52:53], v[144:145] op_sel_hi:[1,0]
	v_pk_mul_f32 v[50:51], v[50:51], v[144:145] op_sel_hi:[1,0]
	v_pk_mul_f32 v[48:49], v[48:49], v[144:145] op_sel_hi:[1,0]
	v_pk_mul_f32 v[46:47], v[46:47], v[144:145] op_sel_hi:[1,0]
	v_pk_mul_f32 v[44:45], v[44:45], v[144:145] op_sel_hi:[1,0]
	v_pk_mul_f32 v[42:43], v[42:43], v[144:145] op_sel_hi:[1,0]
	v_pk_mul_f32 v[40:41], v[40:41], v[144:145] op_sel_hi:[1,0]
	v_pk_mul_f32 v[38:39], v[38:39], v[144:145] op_sel_hi:[1,0]
	v_pk_mul_f32 v[36:37], v[36:37], v[144:145] op_sel_hi:[1,0]
	v_pk_mul_f32 v[34:35], v[34:35], v[144:145] op_sel_hi:[1,0]
	v_pk_mul_f32 v[32:33], v[32:33], v[144:145] op_sel_hi:[1,0]
	v_pk_mul_f32 v[30:31], v[30:31], v[144:145] op_sel_hi:[1,0]
	v_pk_mul_f32 v[28:29], v[28:29], v[144:145] op_sel_hi:[1,0]
	v_pk_mul_f32 v[26:27], v[26:27], v[144:145] op_sel_hi:[1,0]
	v_pk_mul_f32 v[24:25], v[24:25], v[144:145] op_sel_hi:[1,0]
	v_pk_mul_f32 v[22:23], v[22:23], v[144:145] op_sel_hi:[1,0]
	v_pk_mul_f32 v[20:21], v[20:21], v[144:145] op_sel_hi:[1,0]
	v_pk_mul_f32 v[18:19], v[18:19], v[144:145] op_sel_hi:[1,0]
	v_pk_mul_f32 v[16:17], v[16:17], v[144:145] op_sel_hi:[1,0]
	v_sub_f32_e32 v80, v80, v242
	v_sub_f32_e32 v81, v81, v242
	v_sub_f32_e32 v82, v82, v242
	v_sub_f32_e32 v83, v83, v242
	v_sub_f32_e32 v84, v84, v242
	v_sub_f32_e32 v85, v85, v242
	v_sub_f32_e32 v86, v86, v242
	v_sub_f32_e32 v87, v87, v242
	v_sub_f32_e32 v88, v88, v242
	v_sub_f32_e32 v89, v89, v242
	v_sub_f32_e32 v90, v90, v242
	v_sub_f32_e32 v91, v91, v242
	v_sub_f32_e32 v92, v92, v242
	v_sub_f32_e32 v93, v93, v242
	v_sub_f32_e32 v94, v94, v242
	v_sub_f32_e32 v95, v95, v242
	v_sub_f32_e32 v64, v64, v242
	v_sub_f32_e32 v65, v65, v242
	v_sub_f32_e32 v66, v66, v242
	v_sub_f32_e32 v67, v67, v242
	v_sub_f32_e32 v68, v68, v242
	v_sub_f32_e32 v69, v69, v242
	v_sub_f32_e32 v70, v70, v242
	v_sub_f32_e32 v71, v71, v242
	v_sub_f32_e32 v72, v72, v242
	v_sub_f32_e32 v73, v73, v242
	v_sub_f32_e32 v74, v74, v242
	v_sub_f32_e32 v75, v75, v242
	v_sub_f32_e32 v76, v76, v242
	v_sub_f32_e32 v77, v77, v242
	v_sub_f32_e32 v78, v78, v242
	v_sub_f32_e32 v79, v79, v242
	v_sub_f32_e32 v226, v226, v242
	v_sub_f32_e32 v227, v227, v242
	v_sub_f32_e32 v228, v228, v242
	v_sub_f32_e32 v229, v229, v242
	v_sub_f32_e32 v230, v230, v242
	v_sub_f32_e32 v231, v231, v242
	v_sub_f32_e32 v232, v232, v242
	v_sub_f32_e32 v233, v233, v242
	v_sub_f32_e32 v234, v234, v242
	v_sub_f32_e32 v235, v235, v242
	v_sub_f32_e32 v236, v236, v242
	v_sub_f32_e32 v237, v237, v242
	v_sub_f32_e32 v238, v238, v242
	v_sub_f32_e32 v239, v239, v242
	v_sub_f32_e32 v240, v240, v242
	v_sub_f32_e32 v241, v241, v242
	s_branch .LBB0_119

; __device__ __forceinline__ void finishSM(f32x16& p0, f32x16& p1, float alpha, float& l_reg, bf16x8& pa0, bf16x8& pa1, bf16x8& pa2, bf16x8& pa3) {
; #pragma unroll
;   for (int r = 0; r < 16; ++r) p1[r] = __builtin_amdgcn_exp2f(p1[r]);
;   float ps = 0;
; #pragma unroll
;   for (int r = 0; r < 16; ++r) ps += p0[r];
; #pragma unroll
;   for (int r = 0; r < 16; ++r) ps += p1[r];
;   { auto rr = __builtin_amdgcn_permlane32_swap(__float_as_uint(ps), __float_as_uint(ps), false, false);
;     ps = __uint_as_float(rr[0]) + __uint_as_float(rr[1]); }
;   l_reg = l_reg * alpha + ps;
;     ...
;   PK4(p0, 0, pa0); PK4(p0, 8, pa1); PK4(p1, 0, pa2); PK4(p1, 8, pa3);
;     ...
; }
; template <int BUFOFF>
; __device__ __forceinline__ void qkt_diff(f32x16& p0, f32x16& p1, const int* ka, const bf16x8* qr) {
;   typedef __attribute__((address_space(3))) const bf16x8* lp;
;   p0 = f32x16{}; p1 = f32x16{};
; #pragma unroll
;   for (int d0 = 0; d0 < 4; ++d0) {
;     const int a = ka[d0] + BUFOFF;
;     const bf16x8 b0 = *(lp)(a), b1 = *(lp)(a + 8192);
;     p0 = __builtin_amdgcn_mfma_f32_32x32x16_bf16(b0, qr[d0], p0, 0, 0, 0);
;     p1 = __builtin_amdgcn_mfma_f32_32x32x16_bf16(b1, qr[d0], p1, 0, 0, 0);
;   }
; }
.LBB0_129:
	s_mov_b32 s54, s47
	s_mov_b32 s47, s52
	s_add_u32 s4, s14, 0x2000000
	s_addc_u32 s5, s15, 0
	s_mov_b64 s[56:57], s[14:15]
	s_lshl_b32 s52, s53, 14
	s_add_i32 s55, s42, s52
	ds_read_b128 v[64:67], v138 offset:16384
	ds_read_b128 v[68:71], v138 offset:24576
	ds_read_b128 v[170:173], v141 offset:16384
	ds_read_b128 v[188:191], v141 offset:24576
	s_waitcnt lgkmcnt(0)
	v_mfma_f32_32x32x16_bf16 v[80:95], v[64:67], v[108:111], v[226:241]
	v_add_f32_e32 v112, v144, v113
	v_mfma_f32_32x32x16_bf16 v[64:79], v[68:71], v[108:111], v[226:241]
	v_add_f32_e32 v243, v148, v155
	v_add_f32_e32 v244, v145, v152
	v_add_f32_e32 v245, v149, v156
	v_add_f32_e32 v246, v146, v153
	v_add_f32_e32 v247, v150, v158
	v_mfma_f32_32x32x16_bf16 v[80:95], v[170:173], v[104:107], v[80:95]
	v_add_f32_e32 v251, v147, v154
	v_add_f32_e32 v252, v151, v159
	v_mov_b32_e32 v132, v124
	v_add_f32_e32 v112, v128, v112
	v_mov_b32_e32 v162, v125
	v_mfma_f32_32x32x16_bf16 v[64:79], v[188:191], v[104:107], v[64:79]
	ds_read_b128 v[170:173], v140 offset:16384
	ds_read_b128 v[188:191], v140 offset:24576
	v_add_f32_e32 v243, v129, v243
	v_mov_b32_e32 v167, v120
	v_add_f32_e32 v244, v126, v244
	v_mov_b32_e32 v169, v121
	v_add_f32_e32 v245, v127, v245
	v_add_f32_e32 v246, v132, v246
	s_waitcnt lgkmcnt(0)
	v_mfma_f32_32x32x16_bf16 v[80:95], v[170:173], v[100:103], v[80:95]
	v_add_f32_e32 v247, v162, v247
	v_add_f32_e32 v251, v167, v251
	v_add_f32_e32 v252, v169, v252
	v_mfma_f32_32x32x16_bf16 v[64:79], v[188:191], v[100:103], v[64:79]
	ds_read_b128 v[170:173], v139 offset:16384
	ds_read_b128 v[188:191], v139 offset:24576
	s_waitcnt lgkmcnt(0)
	v_mfma_f32_32x32x16_bf16 v[80:95], v[170:173], v[96:99], v[80:95]
	v_mov_b32_e32 v170, v118
	v_mov_b32_e32 v171, v117
	v_mov_b32_e32 v172, v114
	v_mov_b32_e32 v173, v115
	v_add_f32_e32 v112, v170, v112
	v_add_f32_e32 v243, v119, v243
	v_add_f32_e32 v244, v116, v244
	v_mfma_f32_32x32x16_bf16 v[64:79], v[188:191], v[96:99], v[64:79]
	v_mov_b32_e32 v188, v122
	v_mov_b32_e32 v189, v123
	v_add_f32_e32 v245, v171, v245
	v_add_f32_e32 v246, v172, v246
	v_add_f32_e32 v247, v173, v247
	v_add_f32_e32 v251, v188, v251
	v_add_f32_e32 v252, v189, v252
	v_add_f32_e32 v112, v112, v243
	v_add_f32_e32 v244, v244, v245
	v_add_f32_e32 v246, v246, v247
	v_add_f32_e32 v251, v251, v252
	v_add_f32_e32 v112, v112, v244
	v_add_f32_e32 v246, v246, v251
	v_add_f32_e32 v117, v112, v246
	v_mov_b32_e32 v118, v117
	v_cvt_pk_bf16_f32 v112, v113, v155
	v_cvt_pk_bf16_f32 v113, v152, v156
	v_cvt_pk_bf16_f32 v114, v153, v158
	s_nop 1
	v_permlane32_swap_b32_e32 v117, v118
	v_cvt_pk_bf16_f32 v115, v154, v159
	v_cvt_pk_bf16_f32 v120, v144, v148
	v_cvt_pk_bf16_f32 v121, v145, v149
	v_cvt_pk_bf16_f32 v122, v146, v150
	v_cvt_pk_bf16_f32 v123, v147, v151
	v_cvt_pk_bf16_f32 v124, v128, v129
	v_cvt_pk_bf16_f32 v125, v126, v127
	v_cvt_pk_bf16_f32 v126, v132, v162
	v_cvt_pk_bf16_f32 v127, v167, v169
	v_cvt_pk_bf16_f32 v144, v170, v119
	v_cvt_pk_bf16_f32 v145, v116, v171
	v_cvt_pk_bf16_f32 v146, v172, v173
	v_cvt_pk_bf16_f32 v147, v188, v189
	s_mov_b32 m0, s43
	s_nop 0
	global_load_lds_dwordx4 v134, s[56:57]
	s_mov_b32 m0, s44
	s_nop 0
	global_load_lds_dwordx4 v135, s[56:57]
	s_mov_b32 m0, s55
	s_nop 0
	global_load_lds_dwordx4 v136, s[4:5]
	s_add_i32 m0, s55, 0x2000
	s_nop 0
	global_load_lds_dwordx4 v137, s[4:5]
	s_lshl_b32 s55, s47, 14
	v_add_u32_e32 v132, s55, v133
	ds_read_b64_tr_b16 v[148:149], v132 offset:0
	ds_read_b64_tr_b16 v[150:151], v132 offset:0x800
	ds_read_b64_tr_b16 v[152:153], v132 offset:0x1000
	ds_read_b64_tr_b16 v[154:155], v132 offset:0x1800
	ds_read_b64_tr_b16 v[170:171], v132 offset:0x2000
	ds_read_b64_tr_b16 v[172:173], v132 offset:0x2800
	ds_read_b64_tr_b16 v[188:189], v132 offset:0x3000
	ds_read_b64_tr_b16 v[190:191], v132 offset:0x3800
	s_waitcnt lgkmcnt(0)
	s_nop 0
	v_mfma_f32_32x32x16_bf16 v[32:47], v[148:151], v[112:115], v[32:47]
	ds_read_b64_tr_b16 v[148:149], v132 offset:0x200
	ds_read_b64_tr_b16 v[150:151], v132 offset:0xa00
	v_mfma_f32_32x32x16_bf16 v[32:47], v[152:155], v[120:123], v[32:47]
	ds_read_b64_tr_b16 v[152:153], v132 offset:0x1200
	ds_read_b64_tr_b16 v[154:155], v132 offset:0x1a00
	v_mfma_f32_32x32x16_bf16 v[32:47], v[170:173], v[124:127], v[32:47]
	ds_read_b64_tr_b16 v[170:171], v132 offset:0x2200
	ds_read_b64_tr_b16 v[172:173], v132 offset:0x2a00
	v_mfma_f32_32x32x16_bf16 v[32:47], v[188:191], v[144:147], v[32:47]
	ds_read_b64_tr_b16 v[188:189], v132 offset:0x3200
	ds_read_b64_tr_b16 v[190:191], v132 offset:0x3a00
	s_waitcnt lgkmcnt(0)
	v_mfma_f32_32x32x16_bf16 v[48:63], v[148:151], v[112:115], v[48:63]
	ds_read_b64_tr_b16 v[148:149], v132 offset:0x400
	ds_read_b64_tr_b16 v[150:151], v132 offset:0xc00
	v_mfma_f32_32x32x16_bf16 v[48:63], v[152:155], v[120:123], v[48:63]
	ds_read_b64_tr_b16 v[152:153], v132 offset:0x1400
	ds_read_b64_tr_b16 v[154:155], v132 offset:0x1c00
	v_mfma_f32_32x32x16_bf16 v[48:63], v[170:173], v[124:127], v[48:63]
	ds_read_b64_tr_b16 v[170:171], v132 offset:0x2400
	ds_read_b64_tr_b16 v[172:173], v132 offset:0x2c00
	v_mfma_f32_32x32x16_bf16 v[48:63], v[188:191], v[144:147], v[48:63]
	ds_read_b64_tr_b16 v[188:189], v132 offset:0x3400
	ds_read_b64_tr_b16 v[190:191], v132 offset:0x3c00
	s_waitcnt lgkmcnt(0)
	v_mfma_f32_32x32x16_bf16 v[16:31], v[148:151], v[112:115], v[16:31]
	ds_read_b64_tr_b16 v[148:149], v132 offset:0x600
	ds_read_b64_tr_b16 v[150:151], v132 offset:0xe00
	v_mfma_f32_32x32x16_bf16 v[16:31], v[152:155], v[120:123], v[16:31]
	ds_read_b64_tr_b16 v[152:153], v132 offset:0x1600
	ds_read_b64_tr_b16 v[154:155], v132 offset:0x1e00
	v_mfma_f32_32x32x16_bf16 v[16:31], v[170:173], v[124:127], v[16:31]
	ds_read_b64_tr_b16 v[170:171], v132 offset:0x2600
	ds_read_b64_tr_b16 v[172:173], v132 offset:0x2e00
	v_mfma_f32_32x32x16_bf16 v[16:31], v[188:191], v[144:147], v[16:31]
	ds_read_b64_tr_b16 v[188:189], v132 offset:0x3600
	ds_read_b64_tr_b16 v[190:191], v132 offset:0x3e00
	s_waitcnt lgkmcnt(0)
	v_mfma_f32_32x32x16_bf16 v[0:15], v[148:151], v[112:115], v[0:15]
	v_max_f32_e32 v112, v80, v81
	v_max3_f32 v112, v112, v82, v83
	v_max3_f32 v112, v112, v84, v85
	v_max3_f32 v112, v112, v86, v87
	v_max3_f32 v112, v112, v88, v89
	v_max3_f32 v112, v112, v90, v91
	v_max3_f32 v112, v112, v92, v93
	v_mfma_f32_32x32x16_bf16 v[0:15], v[152:155], v[120:123], v[0:15]
	v_max3_f32 v112, v112, v94, v95
	v_max3_f32 v112, v112, v64, v65
	v_max3_f32 v112, v112, v66, v67
	v_max3_f32 v112, v112, v68, v69
	v_max3_f32 v112, v112, v70, v71
	v_max3_f32 v112, v112, v72, v73
	v_max3_f32 v112, v112, v74, v75
	v_max3_f32 v112, v112, v76, v77
	v_mfma_f32_32x32x16_bf16 v[0:15], v[170:173], v[124:127], v[0:15]
	v_max3_f32 v112, v112, v78, v79
	v_mov_b32_e32 v113, v112
	s_nop 1
	v_permlane32_swap_b32_e32 v112, v113
	v_max_f32_e32 v112, v112, v113
	v_cmp_ge_f32_e32 vcc, s70, v112
	v_mfma_f32_32x32x16_bf16 v[0:15], v[188:191], v[144:147], v[0:15]
	s_cmp_eq_u64 vcc, exec
	s_cselect_b64 s[4:5], -1, 0
	s_waitcnt vmcnt(0) lgkmcnt(0)
	s_barrier
; template <int MLA>
; __device__ __forceinline__ void partialSM(f32x16& p0, f32x16& p1, float& m_reg, float& mn, float& alpha) {
;     ...
;   if (__builtin_expect(__all(pmax - m_reg <= THR / SCALE), 1)) { mn = m_reg; alpha = 1.f; }
;   else { mn = fmaxf(m_reg, pmax); alpha = __builtin_amdgcn_exp2f((m_reg - mn) * C); m_reg = mn; }
;   float mnC = -mn * C;
; #pragma unroll
;   for (int r = 0; r < 16; ++r) p0[r] = fmaf(p0[r], C, mnC);
; #pragma unroll
;   for (int r = 0; r < 16; ++r) p1[r] = fmaf(p1[r], C, mnC);
	s_cbranch_scc1 .Lal_c_d1
	v_max_f32_e32 v242, 0, v112
	v_exp_f32_e64 v116, -v242
	s_nop 0
	v_pk_mul_f32 v[46:47], v[46:47], v[116:117] op_sel_hi:[1,0]
	v_pk_mul_f32 v[44:45], v[44:45], v[116:117] op_sel_hi:[1,0]
	v_pk_mul_f32 v[42:43], v[42:43], v[116:117] op_sel_hi:[1,0]
	v_pk_mul_f32 v[40:41], v[40:41], v[116:117] op_sel_hi:[1,0]
	v_pk_mul_f32 v[38:39], v[38:39], v[116:117] op_sel_hi:[1,0]
	v_pk_mul_f32 v[36:37], v[36:37], v[116:117] op_sel_hi:[1,0]
	v_pk_mul_f32 v[34:35], v[34:35], v[116:117] op_sel_hi:[1,0]
	v_pk_mul_f32 v[32:33], v[32:33], v[116:117] op_sel_hi:[1,0]
	v_pk_mul_f32 v[62:63], v[62:63], v[116:117] op_sel_hi:[1,0]
	v_pk_mul_f32 v[60:61], v[60:61], v[116:117] op_sel_hi:[1,0]
	v_pk_mul_f32 v[58:59], v[58:59], v[116:117] op_sel_hi:[1,0]
	v_pk_mul_f32 v[56:57], v[56:57], v[116:117] op_sel_hi:[1,0]
	v_pk_mul_f32 v[54:55], v[54:55], v[116:117] op_sel_hi:[1,0]
	v_pk_mul_f32 v[52:53], v[52:53], v[116:117] op_sel_hi:[1,0]
	v_pk_mul_f32 v[50:51], v[50:51], v[116:117] op_sel_hi:[1,0]
	v_pk_mul_f32 v[48:49], v[48:49], v[116:117] op_sel_hi:[1,0]
	v_pk_mul_f32 v[30:31], v[30:31], v[116:117] op_sel_hi:[1,0]
	v_pk_mul_f32 v[28:29], v[28:29], v[116:117] op_sel_hi:[1,0]
	v_pk_mul_f32 v[26:27], v[26:27], v[116:117] op_sel_hi:[1,0]
	v_pk_mul_f32 v[24:25], v[24:25], v[116:117] op_sel_hi:[1,0]
	v_pk_mul_f32 v[22:23], v[22:23], v[116:117] op_sel_hi:[1,0]
	v_pk_mul_f32 v[20:21], v[20:21], v[116:117] op_sel_hi:[1,0]
	v_pk_mul_f32 v[18:19], v[18:19], v[116:117] op_sel_hi:[1,0]
	v_pk_mul_f32 v[16:17], v[16:17], v[116:117] op_sel_hi:[1,0]
	v_pk_mul_f32 v[14:15], v[14:15], v[116:117] op_sel_hi:[1,0]
	v_pk_mul_f32 v[12:13], v[12:13], v[116:117] op_sel_hi:[1,0]
	v_pk_mul_f32 v[10:11], v[10:11], v[116:117] op_sel_hi:[1,0]
	v_pk_mul_f32 v[8:9], v[8:9], v[116:117] op_sel_hi:[1,0]
	v_pk_mul_f32 v[6:7], v[6:7], v[116:117] op_sel_hi:[1,0]
	v_pk_mul_f32 v[4:5], v[4:5], v[116:117] op_sel_hi:[1,0]
	v_pk_mul_f32 v[2:3], v[2:3], v[116:117] op_sel_hi:[1,0]
	v_pk_mul_f32 v[0:1], v[0:1], v[116:117] op_sel_hi:[1,0]
	v_sub_f32_e32 v80, v80, v242
	v_sub_f32_e32 v81, v81, v242
	v_sub_f32_e32 v82, v82, v242
	v_sub_f32_e32 v83, v83, v242
	v_sub_f32_e32 v84, v84, v242
	v_sub_f32_e32 v85, v85, v242
	v_sub_f32_e32 v86, v86, v242
	v_sub_f32_e32 v87, v87, v242
	v_sub_f32_e32 v88, v88, v242
	v_sub_f32_e32 v89, v89, v242
	v_sub_f32_e32 v90, v90, v242
	v_sub_f32_e32 v91, v91, v242
	v_sub_f32_e32 v92, v92, v242
	v_sub_f32_e32 v93, v93, v242
	v_sub_f32_e32 v94, v94, v242
	v_sub_f32_e32 v95, v95, v242
	v_sub_f32_e32 v64, v64, v242
	v_sub_f32_e32 v65, v65, v242
	v_sub_f32_e32 v66, v66, v242
	v_sub_f32_e32 v67, v67, v242
	v_sub_f32_e32 v68, v68, v242
	v_sub_f32_e32 v69, v69, v242
	v_sub_f32_e32 v70, v70, v242
	v_sub_f32_e32 v71, v71, v242
	v_sub_f32_e32 v72, v72, v242
	v_sub_f32_e32 v73, v73, v242
	v_sub_f32_e32 v74, v74, v242
	v_sub_f32_e32 v75, v75, v242
	v_sub_f32_e32 v76, v76, v242
	v_sub_f32_e32 v77, v77, v242
	v_sub_f32_e32 v78, v78, v242
	v_sub_f32_e32 v79, v79, v242
	v_sub_f32_e32 v226, v226, v242
	v_sub_f32_e32 v227, v227, v242
	v_sub_f32_e32 v228, v228, v242
	v_sub_f32_e32 v229, v229, v242
	v_sub_f32_e32 v230, v230, v242
	v_sub_f32_e32 v231, v231, v242
	v_sub_f32_e32 v232, v232, v242
	v_sub_f32_e32 v233, v233, v242
	v_sub_f32_e32 v234, v234, v242
	v_sub_f32_e32 v235, v235, v242
	v_sub_f32_e32 v236, v236, v242
	v_sub_f32_e32 v237, v237, v242
	v_sub_f32_e32 v238, v238, v242
	v_sub_f32_e32 v239, v239, v242
	v_sub_f32_e32 v240, v240, v242
	v_sub_f32_e32 v241, v241, v242
	s_branch .LBB0_131

; __device__ __forceinline__ void finishSM(f32x16& p0, f32x16& p1, float alpha, float& l_reg, bf16x8& pa0, bf16x8& pa1, bf16x8& pa2, bf16x8& pa3) {
; #pragma unroll
;   for (int r = 0; r < 16; ++r) p1[r] = __builtin_amdgcn_exp2f(p1[r]);
;   float ps = 0;
; #pragma unroll
;   for (int r = 0; r < 16; ++r) ps += p0[r];
; #pragma unroll
;   for (int r = 0; r < 16; ++r) ps += p1[r];
;   { auto rr = __builtin_amdgcn_permlane32_swap(__float_as_uint(ps), __float_as_uint(ps), false, false);
;     ps = __uint_as_float(rr[0]) + __uint_as_float(rr[1]); }
;   l_reg = l_reg * alpha + ps;
;     ...
;   PK4(p0, 0, pa0); PK4(p0, 8, pa1); PK4(p1, 0, pa2); PK4(p1, 8, pa3);
;     ...
; }
; template <int BUFOFF>
; __device__ __forceinline__ void qkt_diff(f32x16& p0, f32x16& p1, const int* ka, const bf16x8* qr) {
;   typedef __attribute__((address_space(3))) const bf16x8* lp;
;   p0 = f32x16{}; p1 = f32x16{};
; #pragma unroll
;   for (int d0 = 0; d0 < 4; ++d0) {
;     const int a = ka[d0] + BUFOFF;
;     const bf16x8 b0 = *(lp)(a), b1 = *(lp)(a + 8192);
;     p0 = __builtin_amdgcn_mfma_f32_32x32x16_bf16(b0, qr[d0], p0, 0, 0, 0);
;     p1 = __builtin_amdgcn_mfma_f32_32x32x16_bf16(b1, qr[d0], p1, 0, 0, 0);
;   }
; }
.LBB0_131:
	s_add_u32 s4, s14, 0x20000
	s_addc_u32 s5, s15, 0
	s_add_u32 s56, s14, 0x2020000
	s_addc_u32 s57, s15, 0
	s_add_i32 s55, s42, s55
	v_exp_f32_e32 v125, v64
	v_exp_f32_e32 v126, v65
	v_exp_f32_e32 v127, v66
	v_exp_f32_e32 v128, v67
	v_exp_f32_e32 v129, v68
	v_exp_f32_e32 v143, v69
	v_exp_f32_e32 v144, v70
	v_exp_f32_e32 v145, v71
	v_exp_f32_e32 v146, v72
	v_exp_f32_e32 v147, v73
	v_exp_f32_e32 v148, v74
	v_exp_f32_e32 v149, v75
	v_exp_f32_e32 v150, v76
	v_exp_f32_e32 v151, v80
	v_exp_f32_e32 v152, v81
	v_exp_f32_e32 v153, v82
	v_exp_f32_e32 v154, v83
	v_exp_f32_e32 v155, v84
	v_exp_f32_e32 v156, v85
	v_exp_f32_e32 v158, v86
	v_exp_f32_e32 v159, v87
	v_exp_f32_e32 v162, v88
	v_exp_f32_e32 v167, v89
	v_exp_f32_e32 v169, v90
	v_exp_f32_e32 v170, v91
	v_exp_f32_e32 v171, v92
	v_exp_f32_e32 v172, v93
	v_exp_f32_e32 v173, v94
	v_exp_f32_e32 v188, v95
	v_exp_f32_e32 v189, v77
	v_exp_f32_e32 v190, v78
	v_exp_f32_e32 v124, v79
	ds_read_b128 v[64:67], v138
	ds_read_b128 v[68:71], v138 offset:8192
	ds_read_b128 v[112:115], v141
	ds_read_b128 v[120:123], v141 offset:8192
	v_mov_b32_e32 v191, v125
	s_waitcnt lgkmcnt(0)
	v_mfma_f32_32x32x16_bf16 v[80:95], v[64:67], v[108:111], v[226:241]
	v_mfma_f32_32x32x16_bf16 v[64:79], v[68:71], v[108:111], v[226:241]
	v_mov_b32_e32 v192, v124
	v_mfma_f32_32x32x16_bf16 v[80:95], v[112:115], v[104:107], v[80:95]
	v_mfma_f32_32x32x16_bf16 v[64:79], v[120:123], v[104:107], v[64:79]
	ds_read_b128 v[112:115], v140
	ds_read_b128 v[120:123], v140 offset:8192
	s_waitcnt lgkmcnt(0)
	v_mfma_f32_32x32x16_bf16 v[80:95], v[112:115], v[100:103], v[80:95]
	v_mfma_f32_32x32x16_bf16 v[64:79], v[120:123], v[100:103], v[64:79]
	ds_read_b128 v[112:115], v139
	ds_read_b128 v[120:123], v139 offset:8192
	s_waitcnt lgkmcnt(0)
	v_mfma_f32_32x32x16_bf16 v[80:95], v[112:115], v[96:99], v[80:95]
	v_add_f32_e32 v112, v162, v151
	v_add_f32_e32 v243, v167, v152
	v_add_f32_e32 v244, v169, v153
	v_add_f32_e32 v245, v170, v154
	v_add_f32_e32 v246, v171, v155
	v_add_f32_e32 v247, v172, v156
	v_add_f32_e32 v251, v173, v158
	v_add_f32_e32 v252, v188, v159
	v_add_f32_e32 v112, v191, v112
	v_add_f32_e32 v243, v126, v243
	v_add_f32_e32 v244, v127, v244
	v_add_f32_e32 v245, v128, v245
	v_add_f32_e32 v246, v129, v246
	v_add_f32_e32 v247, v143, v247
	v_add_f32_e32 v251, v144, v251
	v_add_f32_e32 v252, v145, v252
	v_add_f32_e32 v112, v146, v112
	v_add_f32_e32 v243, v147, v243
	v_mfma_f32_32x32x16_bf16 v[64:79], v[120:123], v[96:99], v[64:79]
	v_add_f32_e32 v244, v148, v244
	v_add_f32_e32 v245, v149, v245
	v_add_f32_e32 v246, v150, v246
	v_add_f32_e32 v247, v189, v247
	v_add_f32_e32 v251, v190, v251
	v_add_f32_e32 v252, v192, v252
	v_add_f32_e32 v112, v112, v243
	v_add_f32_e32 v244, v244, v245
	v_add_f32_e32 v246, v246, v247
	v_add_f32_e32 v251, v251, v252
	v_add_f32_e32 v112, v112, v244
	v_add_f32_e32 v246, v246, v251
	v_add_f32_e32 v120, v112, v246
	v_mov_b32_e32 v121, v120
	v_cvt_pk_bf16_f32 v112, v151, v152
	v_cvt_pk_bf16_f32 v113, v153, v154
	v_cvt_pk_bf16_f32 v114, v155, v156
	v_cvt_pk_bf16_f32 v115, v158, v159
	s_nop 1
	v_permlane32_swap_b32_e32 v120, v121
	v_cvt_pk_bf16_f32 v122, v162, v167
	v_cvt_pk_bf16_f32 v123, v169, v170
	v_cvt_pk_bf16_f32 v124, v171, v172
	v_cvt_pk_bf16_f32 v125, v173, v188
	v_cvt_pk_bf16_f32 v126, v191, v126
	v_cvt_pk_bf16_f32 v127, v127, v128
	v_cvt_pk_bf16_f32 v128, v129, v143
	v_cvt_pk_bf16_f32 v129, v144, v145
	v_cvt_pk_bf16_f32 v144, v146, v147
	v_cvt_pk_bf16_f32 v145, v148, v149
	v_cvt_pk_bf16_f32 v146, v150, v189
	v_cvt_pk_bf16_f32 v147, v190, v192
	s_nop 0
	s_mov_b32 m0, s16
	s_nop 0
	global_load_lds_dwordx4 v134, s[4:5]
	s_mov_b32 m0, s17
	s_nop 0
	global_load_lds_dwordx4 v135, s[4:5]
	s_mov_b32 m0, s55
	s_nop 0
	global_load_lds_dwordx4 v136, s[56:57]
	s_add_i32 m0, s55, 0x2000
	s_nop 0
	global_load_lds_dwordx4 v137, s[56:57]
	v_lshl_add_u32 v143, s54, 14, v133
	ds_read_b64_tr_b16 v[148:149], v143 offset:0
	ds_read_b64_tr_b16 v[150:151], v143 offset:0x800
	ds_read_b64_tr_b16 v[152:153], v143 offset:0x1000
	ds_read_b64_tr_b16 v[154:155], v143 offset:0x1800
	ds_read_b64_tr_b16 v[170:171], v143 offset:0x2000
	ds_read_b64_tr_b16 v[172:173], v143 offset:0x2800
	ds_read_b64_tr_b16 v[188:189], v143 offset:0x3000
	ds_read_b64_tr_b16 v[190:191], v143 offset:0x3800
	s_waitcnt lgkmcnt(0)
	s_nop 0
	v_mfma_f32_32x32x16_bf16 v[32:47], v[148:151], v[112:115], v[32:47]
	ds_read_b64_tr_b16 v[148:149], v143 offset:0x200
	ds_read_b64_tr_b16 v[150:151], v143 offset:0xa00
	v_mfma_f32_32x32x16_bf16 v[32:47], v[152:155], v[122:125], v[32:47]
	ds_read_b64_tr_b16 v[152:153], v143 offset:0x1200
	ds_read_b64_tr_b16 v[154:155], v143 offset:0x1a00
	v_mfma_f32_32x32x16_bf16 v[32:47], v[170:173], v[126:129], v[32:47]
	ds_read_b64_tr_b16 v[170:171], v143 offset:0x2200
	ds_read_b64_tr_b16 v[172:173], v143 offset:0x2a00
	v_mfma_f32_32x32x16_bf16 v[32:47], v[188:191], v[144:147], v[32:47]
	ds_read_b64_tr_b16 v[188:189], v143 offset:0x3200
	ds_read_b64_tr_b16 v[190:191], v143 offset:0x3a00
	s_waitcnt lgkmcnt(0)
	v_mfma_f32_32x32x16_bf16 v[48:63], v[148:151], v[112:115], v[48:63]
	ds_read_b64_tr_b16 v[148:149], v143 offset:0x400
	ds_read_b64_tr_b16 v[150:151], v143 offset:0xc00
	v_mfma_f32_32x32x16_bf16 v[48:63], v[152:155], v[122:125], v[48:63]
	ds_read_b64_tr_b16 v[152:153], v143 offset:0x1400
	ds_read_b64_tr_b16 v[154:155], v143 offset:0x1c00
	v_mfma_f32_32x32x16_bf16 v[48:63], v[170:173], v[126:129], v[48:63]
	ds_read_b64_tr_b16 v[170:171], v143 offset:0x2400
	ds_read_b64_tr_b16 v[172:173], v143 offset:0x2c00
	v_mfma_f32_32x32x16_bf16 v[48:63], v[188:191], v[144:147], v[48:63]
	ds_read_b64_tr_b16 v[188:189], v143 offset:0x3400
	ds_read_b64_tr_b16 v[190:191], v143 offset:0x3c00
	s_waitcnt lgkmcnt(0)
; #define SBAR() __builtin_amdgcn_sched_barrier(0)
; template <int MLA>
; __device__ __forceinline__ void partialSM(f32x16& p0, f32x16& p1, float& m_reg, float& mn, float& alpha) {
;     ...
;   float pmax = p0[0];
; #pragma unroll
;   for (int r = 1; r < 16; ++r) pmax = fmaxf(pmax, p0[r]);
; #pragma unroll
;   for (int r = 0; r < 16; ++r) pmax = fmaxf(pmax, p1[r]);
;   { auto rr = __builtin_amdgcn_permlane32_swap(__float_as_uint(pmax), __float_as_uint(pmax), false, false);
;     pmax = fmaxf(__uint_as_float(rr[0]), __uint_as_float(rr[1])); }
;   if (__builtin_expect(__all(pmax - m_reg <= THR / SCALE), 1)) { mn = m_reg; alpha = 1.f; }
;   else { mn = fmaxf(m_reg, pmax); alpha = __builtin_amdgcn_exp2f((m_reg - mn) * C); m_reg = mn; }
; template <int D0> __device__ __forceinline__ void pv_one_t(f32x16& od, int vb, bf16x8 pa0, bf16x8 pa1, bf16x8 pa2, bf16x8 pa3) {
;   const s16x4 l0 = tr_read<v_rd_off(D0, 0, 0)>(vb), h0 = tr_read<v_rd_off(D0, 0, 1)>(vb), l1 = tr_read<v_rd_off(D0, 1, 0)>(vb), h1 = tr_read<v_rd_off(D0, 1, 1)>(vb);
;   const s16x4 l2 = tr_read<v_rd_off(D0, 2, 0)>(vb), h2 = tr_read<v_rd_off(D0, 2, 1)>(vb), l3 = tr_read<v_rd_off(D0, 3, 0)>(vb), h3 = tr_read<v_rd_off(D0, 3, 1)>(vb);
;   asm volatile("s_waitcnt lgkmcnt(0)" ::: "memory"); SBAR();
;     ...
;   od = __builtin_amdgcn_mfma_f32_32x32x16_bf16(PK(l0, h0), pa0, od, 0, 0, 0);
;   od = __builtin_amdgcn_mfma_f32_32x32x16_bf16(PK(l1, h1), pa1, od, 0, 0, 0);
;   od = __builtin_amdgcn_mfma_f32_32x32x16_bf16(PK(l2, h2), pa2, od, 0, 0, 0);
;   od = __builtin_amdgcn_mfma_f32_32x32x16_bf16(PK(l3, h3), pa3, od, 0, 0, 0);
;     ...
; }
	v_mfma_f32_32x32x16_bf16 v[16:31], v[148:151], v[112:115], v[16:31]
	ds_read_b64_tr_b16 v[148:149], v143 offset:0x600
	ds_read_b64_tr_b16 v[150:151], v143 offset:0xe00
	v_mfma_f32_32x32x16_bf16 v[16:31], v[152:155], v[122:125], v[16:31]
	ds_read_b64_tr_b16 v[152:153], v143 offset:0x1600
	ds_read_b64_tr_b16 v[154:155], v143 offset:0x1e00
	v_mfma_f32_32x32x16_bf16 v[16:31], v[170:173], v[126:129], v[16:31]
	ds_read_b64_tr_b16 v[170:171], v143 offset:0x2600
	ds_read_b64_tr_b16 v[172:173], v143 offset:0x2e00
	v_mfma_f32_32x32x16_bf16 v[16:31], v[188:191], v[144:147], v[16:31]
	ds_read_b64_tr_b16 v[188:189], v143 offset:0x3600
	ds_read_b64_tr_b16 v[190:191], v143 offset:0x3e00
	s_waitcnt lgkmcnt(0)
	v_mfma_f32_32x32x16_bf16 v[0:15], v[148:151], v[112:115], v[0:15]
	v_max_f32_e32 v112, v80, v81
	v_max3_f32 v112, v112, v82, v83
	v_max3_f32 v112, v112, v84, v85
	v_max3_f32 v112, v112, v86, v87
	v_max3_f32 v112, v112, v88, v89
	v_max3_f32 v112, v112, v90, v91
	v_max3_f32 v112, v112, v92, v93
	v_mfma_f32_32x32x16_bf16 v[0:15], v[152:155], v[122:125], v[0:15]
	v_max3_f32 v112, v112, v94, v95
	v_max3_f32 v112, v112, v64, v65
	v_max3_f32 v112, v112, v66, v67
	v_max3_f32 v112, v112, v68, v69
	v_max3_f32 v112, v112, v70, v71
	v_max3_f32 v112, v112, v72, v73
	v_max3_f32 v112, v112, v74, v75
	v_max3_f32 v112, v112, v76, v77
	v_mfma_f32_32x32x16_bf16 v[0:15], v[170:173], v[126:129], v[0:15]
	v_max3_f32 v112, v112, v78, v79
	v_mov_b32_e32 v113, v112
	s_nop 1
	v_permlane32_swap_b32_e32 v112, v113
	v_max_f32_e32 v112, v112, v113
	v_cmp_ge_f32_e32 vcc, s70, v112
	v_mfma_f32_32x32x16_bf16 v[0:15], v[188:191], v[144:147], v[0:15]
	s_cmp_eq_u64 vcc, exec
	s_cselect_b64 s[4:5], -1, 0
	s_waitcnt vmcnt(0) lgkmcnt(0)
	s_barrier
	s_cbranch_scc1 .Lal_c_d2
	v_max_f32_e32 v242, 0, v112
	v_exp_f32_e64 v112, -v242
	s_nop 0
	v_pk_mul_f32 v[46:47], v[46:47], v[112:113] op_sel_hi:[1,0]
	v_pk_mul_f32 v[44:45], v[44:45], v[112:113] op_sel_hi:[1,0]
	v_pk_mul_f32 v[42:43], v[42:43], v[112:113] op_sel_hi:[1,0]
	v_pk_mul_f32 v[40:41], v[40:41], v[112:113] op_sel_hi:[1,0]
	v_pk_mul_f32 v[38:39], v[38:39], v[112:113] op_sel_hi:[1,0]
	v_pk_mul_f32 v[36:37], v[36:37], v[112:113] op_sel_hi:[1,0]
	v_pk_mul_f32 v[34:35], v[34:35], v[112:113] op_sel_hi:[1,0]
	v_pk_mul_f32 v[32:33], v[32:33], v[112:113] op_sel_hi:[1,0]
	v_pk_mul_f32 v[62:63], v[62:63], v[112:113] op_sel_hi:[1,0]
	v_pk_mul_f32 v[60:61], v[60:61], v[112:113] op_sel_hi:[1,0]
	v_pk_mul_f32 v[58:59], v[58:59], v[112:113] op_sel_hi:[1,0]
	v_pk_mul_f32 v[56:57], v[56:57], v[112:113] op_sel_hi:[1,0]
	v_pk_mul_f32 v[54:55], v[54:55], v[112:113] op_sel_hi:[1,0]
	v_pk_mul_f32 v[52:53], v[52:53], v[112:113] op_sel_hi:[1,0]
	v_pk_mul_f32 v[50:51], v[50:51], v[112:113] op_sel_hi:[1,0]
	v_pk_mul_f32 v[48:49], v[48:49], v[112:113] op_sel_hi:[1,0]
	v_pk_mul_f32 v[30:31], v[30:31], v[112:113] op_sel_hi:[1,0]
	v_pk_mul_f32 v[28:29], v[28:29], v[112:113] op_sel_hi:[1,0]
	v_pk_mul_f32 v[26:27], v[26:27], v[112:113] op_sel_hi:[1,0]
	v_pk_mul_f32 v[24:25], v[24:25], v[112:113] op_sel_hi:[1,0]
	v_pk_mul_f32 v[22:23], v[22:23], v[112:113] op_sel_hi:[1,0]
	v_pk_mul_f32 v[20:21], v[20:21], v[112:113] op_sel_hi:[1,0]
	v_pk_mul_f32 v[18:19], v[18:19], v[112:113] op_sel_hi:[1,0]
	v_pk_mul_f32 v[16:17], v[16:17], v[112:113] op_sel_hi:[1,0]
	v_pk_mul_f32 v[14:15], v[14:15], v[112:113] op_sel_hi:[1,0]
	v_pk_mul_f32 v[12:13], v[12:13], v[112:113] op_sel_hi:[1,0]
	v_pk_mul_f32 v[10:11], v[10:11], v[112:113] op_sel_hi:[1,0]
	v_pk_mul_f32 v[8:9], v[8:9], v[112:113] op_sel_hi:[1,0]
	v_pk_mul_f32 v[6:7], v[6:7], v[112:113] op_sel_hi:[1,0]
	v_pk_mul_f32 v[4:5], v[4:5], v[112:113] op_sel_hi:[1,0]
	v_pk_mul_f32 v[2:3], v[2:3], v[112:113] op_sel_hi:[1,0]
	v_pk_mul_f32 v[0:1], v[0:1], v[112:113] op_sel_hi:[1,0]
	v_sub_f32_e32 v80, v80, v242
	v_sub_f32_e32 v81, v81, v242
	v_sub_f32_e32 v82, v82, v242
	v_sub_f32_e32 v83, v83, v242
	v_sub_f32_e32 v84, v84, v242
	v_sub_f32_e32 v85, v85, v242
	v_sub_f32_e32 v86, v86, v242
	v_sub_f32_e32 v87, v87, v242
	v_sub_f32_e32 v88, v88, v242
	v_sub_f32_e32 v89, v89, v242
	v_sub_f32_e32 v90, v90, v242
	v_sub_f32_e32 v91, v91, v242
	v_sub_f32_e32 v92, v92, v242
	v_sub_f32_e32 v93, v93, v242
	v_sub_f32_e32 v94, v94, v242
	v_sub_f32_e32 v95, v95, v242
	v_sub_f32_e32 v64, v64, v242
	v_sub_f32_e32 v65, v65, v242
	v_sub_f32_e32 v66, v66, v242
	v_sub_f32_e32 v67, v67, v242
	v_sub_f32_e32 v68, v68, v242
	v_sub_f32_e32 v69, v69, v242
	v_sub_f32_e32 v70, v70, v242
	v_sub_f32_e32 v71, v71, v242
	v_sub_f32_e32 v72, v72, v242
	v_sub_f32_e32 v73, v73, v242
	v_sub_f32_e32 v74, v74, v242
	v_sub_f32_e32 v75, v75, v242
	v_sub_f32_e32 v76, v76, v242
	v_sub_f32_e32 v77, v77, v242
	v_sub_f32_e32 v78, v78, v242
	v_sub_f32_e32 v79, v79, v242
	v_sub_f32_e32 v226, v226, v242
	v_sub_f32_e32 v227, v227, v242
	v_sub_f32_e32 v228, v228, v242
	v_sub_f32_e32 v229, v229, v242
	v_sub_f32_e32 v230, v230, v242
	v_sub_f32_e32 v231, v231, v242
	v_sub_f32_e32 v232, v232, v242
	v_sub_f32_e32 v233, v233, v242
	v_sub_f32_e32 v234, v234, v242
	v_sub_f32_e32 v235, v235, v242
	v_sub_f32_e32 v236, v236, v242
	v_sub_f32_e32 v237, v237, v242
	v_sub_f32_e32 v238, v238, v242
	v_sub_f32_e32 v239, v239, v242
	v_sub_f32_e32 v240, v240, v242
	v_sub_f32_e32 v241, v241, v242
	s_branch .LBB0_133
